# grid barrier: last workgroup of an XCD adds to the top arrival counter without waiting for the return; all workgroups poll that counter (no top-level returning atomic, no generation words)
# baseline (speedup 1.0000x reference)
; __device__ __forceinline__ unsigned xb_ld(unsigned* p)              { return __hip_atomic_load(p, __ATOMIC_RELAXED, __HIP_MEMORY_SCOPE_AGENT); }
; __device__ __forceinline__ unsigned xb_add(unsigned* p, unsigned v) { return __hip_atomic_fetch_add(p, v, __ATOMIC_RELAXED, __HIP_MEMORY_SCOPE_AGENT); }
; #define XB_SPIN(cond, bar) do { unsigned _sp = 0; while (cond) { __builtin_amdgcn_s_sleep(1); \
;     if ((++_sp & 255u) == 0u) { if (xb_ld(&(bar)[XB_TMO])) break; if (_sp > XB_SPIN_CAP) { atomicAdd(&(bar)[XB_TMO], 1u); break; } } } } while (0)
; __device__ __forceinline__ void xcd_barrier(const XcdBarrier& b) {
;     ...
;         const unsigned old = xb_add(&bar[XB_XSUB(b.x)], 1u);
;         const unsigned gen = old / nloc;
;         if (old + 1u == (gen + 1u) * nloc) {
;             __builtin_amdgcn_fence(__ATOMIC_RELEASE, "agent");
;             asm volatile("s_waitcnt vmcnt(0)" ::: "memory");
;             const unsigned og = xb_add(&bar[XB_TOP], 1u);
;             const unsigned tg = og / nx;
;             if (og + 1u == (tg + 1u) * nx) xb_add(&bar[XB_TOPGEN], 1u);
;             else XB_SPIN(xb_ld(&bar[XB_TOPGEN]) == tg, bar);
;             __builtin_amdgcn_fence(__ATOMIC_ACQUIRE, "agent");
;             xb_add(&bar[XB_XGEN(b.x)], 1u);
;             asm volatile("s_waitcnt vmcnt(0)" ::: "memory");
;         } else {
;             XB_SPIN(xb_ld(&bar[XB_XGEN(b.x)]) == gen, bar);
;             __builtin_amdgcn_fence(__ATOMIC_ACQUIRE, "agent");
;             asm volatile("s_waitcnt vmcnt(0)" ::: "memory");
;         }
.LBB0_64:
	s_or_b64 exec, exec, s[16:17]
	v_cvt_f32_u32_e32 v5, v3
	s_waitcnt vmcnt(0)
	v_readfirstlane_b32 s6, v4
	v_sub_u32_e32 v4, 0, v3
	v_rcp_iflag_f32_e32 v5, v5
	v_add_u32_e32 v6, s6, v2
	v_mul_f32_e32 v5, 0x4f7ffffe, v5
	v_cvt_u32_f32_e32 v5, v5
	v_mul_lo_u32 v2, v4, v5
	v_mul_hi_u32 v2, v5, v2
	v_add_u32_e32 v2, v5, v2
	v_mul_hi_u32 v2, v6, v2
	v_mul_lo_u32 v4, v2, v3
	v_sub_u32_e32 v4, v6, v4
	v_add_u32_e32 v5, 1, v2
	v_cmp_ge_u32_e32 vcc, v4, v3
	s_nop 1
	v_cndmask_b32_e32 v2, v2, v5, vcc
	v_sub_u32_e32 v5, v4, v3
	v_cndmask_b32_e32 v4, v4, v5, vcc
	v_add_u32_e32 v5, 1, v2
	v_cmp_ge_u32_e32 vcc, v4, v3
	v_add_u32_e32 v4, 1, v6
	s_nop 0
	v_cndmask_b32_e32 v2, v2, v5, vcc
	v_mul_lo_u32 v5, v3, v2
	v_add_u32_e32 v3, v5, v3
	v_cmp_ne_u32_e32 vcc, v4, v3
	s_cbranch_vccnz .Lxb_nl_0
	buffer_wbl2 sc1
	s_waitcnt vmcnt(0) lgkmcnt(0)
	v_mov_b32_e32 v4, 0x3400
	v_mov_b32_e32 v3, 1
	global_atomic_add v4, v3, s[48:49]
.Lxb_nl_0:
	s_mov_b64 vcc, exec
	s_and_saveexec_b64 s[6:7], vcc
	s_xor_b64 s[14:15], exec, s[6:7]
	s_cbranch_execz .LBB0_78
	s_waitcnt lgkmcnt(0)
	v_add_u32_e32 v2, 1, v2
	v_mul_lo_u32 v2, v2, v1
	v_mov_b32_e32 v1, 0x3400
	global_load_dword v1, v1, s[48:49] sc1
	s_add_u32 s18, s48, 0x3400
	s_addc_u32 s19, s49, 0
	s_waitcnt vmcnt(0)
	v_cmp_lt_u32_e32 vcc, v1, v2
	s_and_saveexec_b64 s[16:17], vcc
	s_cbranch_execz .LBB0_77
	s_mov_b32 s6, 1
	s_mov_b64 s[20:21], 0
	v_mov_b32_e32 v1, 0
	s_branch .LBB0_68

; __device__ __forceinline__ unsigned xb_ld(unsigned* p)              { return __hip_atomic_load(p, __ATOMIC_RELAXED, __HIP_MEMORY_SCOPE_AGENT); }
; #define XB_SPIN(cond, bar) do { unsigned _sp = 0; while (cond) { __builtin_amdgcn_s_sleep(1); \
;     if ((++_sp & 255u) == 0u) { if (xb_ld(&(bar)[XB_TMO])) break; if (_sp > XB_SPIN_CAP) { atomicAdd(&(bar)[XB_TMO], 1u); break; } } } } while (0)
; __device__ __forceinline__ void xcd_barrier(const XcdBarrier& b) {
;     ...
;             XB_SPIN(xb_ld(&bar[XB_XGEN(b.x)]) == gen, bar);
.LBB0_70:
	global_load_dword v3, v1, s[18:19] sc1
	s_add_i32 s6, s6, 1
	s_mov_b64 s[26:27], -1
	s_waitcnt vmcnt(0)
	v_cmp_ge_u32_e32 vcc, v3, v2
	s_orn2_b64 s[24:25], vcc, exec
	s_branch .LBB0_67

; __device__ __forceinline__ unsigned xb_ld(unsigned* p)              { return __hip_atomic_load(p, __ATOMIC_RELAXED, __HIP_MEMORY_SCOPE_AGENT); }
; __device__ __forceinline__ unsigned xb_add(unsigned* p, unsigned v) { return __hip_atomic_fetch_add(p, v, __ATOMIC_RELAXED, __HIP_MEMORY_SCOPE_AGENT); }
; #define XB_SPIN(cond, bar) do { unsigned _sp = 0; while (cond) { __builtin_amdgcn_s_sleep(1); \
;     if ((++_sp & 255u) == 0u) { if (xb_ld(&(bar)[XB_TMO])) break; if (_sp > XB_SPIN_CAP) { atomicAdd(&(bar)[XB_TMO], 1u); break; } } } } while (0)
; __device__ __forceinline__ void xcd_barrier(const XcdBarrier& b) {
;     ...
;         const unsigned old = xb_add(&bar[XB_XSUB(b.x)], 1u);
;         const unsigned gen = old / nloc;
;         if (old + 1u == (gen + 1u) * nloc) {
;             __builtin_amdgcn_fence(__ATOMIC_RELEASE, "agent");
;             asm volatile("s_waitcnt vmcnt(0)" ::: "memory");
;             const unsigned og = xb_add(&bar[XB_TOP], 1u);
;             const unsigned tg = og / nx;
;             if (og + 1u == (tg + 1u) * nx) xb_add(&bar[XB_TOPGEN], 1u);
;             else XB_SPIN(xb_ld(&bar[XB_TOPGEN]) == tg, bar);
;             __builtin_amdgcn_fence(__ATOMIC_ACQUIRE, "agent");
;             xb_add(&bar[XB_XGEN(b.x)], 1u);
;             asm volatile("s_waitcnt vmcnt(0)" ::: "memory");
;         } else {
;             XB_SPIN(xb_ld(&bar[XB_XGEN(b.x)]) == gen, bar);
;             __builtin_amdgcn_fence(__ATOMIC_ACQUIRE, "agent");
;             asm volatile("s_waitcnt vmcnt(0)" ::: "memory");
;         }
.LBB0_183:
	s_or_b64 exec, exec, s[14:15]
	v_cvt_f32_u32_e32 v4, v2
	s_waitcnt vmcnt(0)
	v_readfirstlane_b32 s6, v3
	v_sub_u32_e32 v3, 0, v2
	v_rcp_iflag_f32_e32 v4, v4
	v_add_u32_e32 v5, s6, v1
	v_mul_f32_e32 v4, 0x4f7ffffe, v4
	v_cvt_u32_f32_e32 v4, v4
	v_mul_lo_u32 v1, v3, v4
	v_mul_hi_u32 v1, v4, v1
	v_add_u32_e32 v1, v4, v1
	v_mul_hi_u32 v1, v5, v1
	v_mul_lo_u32 v3, v1, v2
	v_sub_u32_e32 v3, v5, v3
	v_add_u32_e32 v4, 1, v1
	v_cmp_ge_u32_e32 vcc, v3, v2
	s_nop 1
	v_cndmask_b32_e32 v1, v1, v4, vcc
	v_sub_u32_e32 v4, v3, v2
	v_cndmask_b32_e32 v3, v3, v4, vcc
	v_add_u32_e32 v4, 1, v1
	v_cmp_ge_u32_e32 vcc, v3, v2
	v_add_u32_e32 v3, 1, v5
	s_nop 0
	v_cndmask_b32_e32 v1, v1, v4, vcc
	v_mul_lo_u32 v4, v2, v1
	v_add_u32_e32 v2, v4, v2
	v_cmp_ne_u32_e32 vcc, v3, v2
	s_cbranch_vccnz .Lxb_nl_1
	buffer_wbl2 sc1
	s_waitcnt vmcnt(0) lgkmcnt(0)
	v_mov_b32_e32 v3, 0x3400
	v_mov_b32_e32 v2, 1
	global_atomic_add v3, v2, s[48:49]
.Lxb_nl_1:
	s_mov_b64 vcc, exec
	s_and_saveexec_b64 s[6:7], vcc
	s_xor_b64 s[12:13], exec, s[6:7]
	s_cbranch_execz .LBB0_197
	s_waitcnt lgkmcnt(0)
	v_add_u32_e32 v1, 1, v1
	v_mul_lo_u32 v1, v1, v0
	v_mov_b32_e32 v0, 0x3400
	global_load_dword v0, v0, s[48:49] sc1
	s_add_u32 s16, s48, 0x3400
	s_addc_u32 s17, s49, 0
	s_waitcnt vmcnt(0)
	v_cmp_lt_u32_e32 vcc, v0, v1
	s_and_saveexec_b64 s[14:15], vcc
	s_cbranch_execz .LBB0_196
	s_mov_b32 s6, 1
	s_mov_b64 s[18:19], 0
	v_mov_b32_e32 v0, 0
	s_branch .LBB0_187

; __device__ __forceinline__ unsigned xb_ld(unsigned* p)              { return __hip_atomic_load(p, __ATOMIC_RELAXED, __HIP_MEMORY_SCOPE_AGENT); }
; #define XB_SPIN(cond, bar) do { unsigned _sp = 0; while (cond) { __builtin_amdgcn_s_sleep(1); \
;     if ((++_sp & 255u) == 0u) { if (xb_ld(&(bar)[XB_TMO])) break; if (_sp > XB_SPIN_CAP) { atomicAdd(&(bar)[XB_TMO], 1u); break; } } } } while (0)
; __device__ __forceinline__ void xcd_barrier(const XcdBarrier& b) {
;     ...
;             XB_SPIN(xb_ld(&bar[XB_XGEN(b.x)]) == gen, bar);
.LBB0_189:
	global_load_dword v2, v0, s[16:17] sc1
	s_add_i32 s6, s6, 1
	s_mov_b64 s[24:25], -1
	s_waitcnt vmcnt(0)
	v_cmp_ge_u32_e32 vcc, v2, v1
	s_orn2_b64 s[22:23], vcc, exec
	s_branch .LBB0_186

; __device__ __forceinline__ unsigned xb_ld(unsigned* p)              { return __hip_atomic_load(p, __ATOMIC_RELAXED, __HIP_MEMORY_SCOPE_AGENT); }
; __device__ __forceinline__ unsigned xb_add(unsigned* p, unsigned v) { return __hip_atomic_fetch_add(p, v, __ATOMIC_RELAXED, __HIP_MEMORY_SCOPE_AGENT); }
; #define XB_SPIN(cond, bar) do { unsigned _sp = 0; while (cond) { __builtin_amdgcn_s_sleep(1); \
;     if ((++_sp & 255u) == 0u) { if (xb_ld(&(bar)[XB_TMO])) break; if (_sp > XB_SPIN_CAP) { atomicAdd(&(bar)[XB_TMO], 1u); break; } } } } while (0)
; __device__ __forceinline__ void xcd_barrier(const XcdBarrier& b) {
;     ...
;         const unsigned old = xb_add(&bar[XB_XSUB(b.x)], 1u);
;         const unsigned gen = old / nloc;
;         if (old + 1u == (gen + 1u) * nloc) {
;             __builtin_amdgcn_fence(__ATOMIC_RELEASE, "agent");
;             asm volatile("s_waitcnt vmcnt(0)" ::: "memory");
;             const unsigned og = xb_add(&bar[XB_TOP], 1u);
;             const unsigned tg = og / nx;
;             if (og + 1u == (tg + 1u) * nx) xb_add(&bar[XB_TOPGEN], 1u);
;             else XB_SPIN(xb_ld(&bar[XB_TOPGEN]) == tg, bar);
;             __builtin_amdgcn_fence(__ATOMIC_ACQUIRE, "agent");
;             xb_add(&bar[XB_XGEN(b.x)], 1u);
;             asm volatile("s_waitcnt vmcnt(0)" ::: "memory");
;         } else {
;             XB_SPIN(xb_ld(&bar[XB_XGEN(b.x)]) == gen, bar);
;             __builtin_amdgcn_fence(__ATOMIC_ACQUIRE, "agent");
;             asm volatile("s_waitcnt vmcnt(0)" ::: "memory");
;         }
.LBB0_561:
	s_or_b64 exec, exec, s[16:17]
	v_cvt_f32_u32_e32 v4, v2
	s_waitcnt vmcnt(0)
	v_readfirstlane_b32 s6, v3
	v_sub_u32_e32 v3, 0, v2
	v_rcp_iflag_f32_e32 v4, v4
	v_add_u32_e32 v5, s6, v1
	v_mul_f32_e32 v4, 0x4f7ffffe, v4
	v_cvt_u32_f32_e32 v4, v4
	v_mul_lo_u32 v1, v3, v4
	v_mul_hi_u32 v1, v4, v1
	v_add_u32_e32 v1, v4, v1
	v_mul_hi_u32 v1, v5, v1
	v_mul_lo_u32 v3, v1, v2
	v_sub_u32_e32 v3, v5, v3
	v_add_u32_e32 v4, 1, v1
	v_cmp_ge_u32_e32 vcc, v3, v2
	s_nop 1
	v_cndmask_b32_e32 v1, v1, v4, vcc
	v_sub_u32_e32 v4, v3, v2
	v_cndmask_b32_e32 v3, v3, v4, vcc
	v_add_u32_e32 v4, 1, v1
	v_cmp_ge_u32_e32 vcc, v3, v2
	v_add_u32_e32 v3, 1, v5
	s_nop 0
	v_cndmask_b32_e32 v1, v1, v4, vcc
	v_mul_lo_u32 v4, v2, v1
	v_add_u32_e32 v2, v4, v2
	v_cmp_ne_u32_e32 vcc, v3, v2
	s_cbranch_vccnz .Lxb_nl_4
	buffer_wbl2 sc1
	s_waitcnt vmcnt(0) lgkmcnt(0)
	v_mov_b32_e32 v3, 0x3400
	v_mov_b32_e32 v2, 1
	global_atomic_add v3, v2, s[48:49]
.Lxb_nl_4:
	s_mov_b64 vcc, exec
	s_and_saveexec_b64 s[6:7], vcc
	s_xor_b64 s[14:15], exec, s[6:7]
	s_cbranch_execz .LBB0_575
	s_waitcnt lgkmcnt(0)
	v_add_u32_e32 v1, 1, v1
	v_mul_lo_u32 v1, v1, v0
	v_mov_b32_e32 v0, 0x3400
	global_load_dword v0, v0, s[48:49] sc1
	s_add_u32 s18, s48, 0x3400
	s_addc_u32 s19, s49, 0
	s_waitcnt vmcnt(0)
	v_cmp_lt_u32_e32 vcc, v0, v1
	s_and_saveexec_b64 s[16:17], vcc
	s_cbranch_execz .LBB0_574
	s_mov_b32 s6, 1
	s_mov_b64 s[20:21], 0
	v_mov_b32_e32 v0, 0
	s_branch .LBB0_565

; __device__ __forceinline__ unsigned xb_ld(unsigned* p)              { return __hip_atomic_load(p, __ATOMIC_RELAXED, __HIP_MEMORY_SCOPE_AGENT); }
; #define XB_SPIN(cond, bar) do { unsigned _sp = 0; while (cond) { __builtin_amdgcn_s_sleep(1); \
;     if ((++_sp & 255u) == 0u) { if (xb_ld(&(bar)[XB_TMO])) break; if (_sp > XB_SPIN_CAP) { atomicAdd(&(bar)[XB_TMO], 1u); break; } } } } while (0)
; __device__ __forceinline__ void xcd_barrier(const XcdBarrier& b) {
;     ...
;             XB_SPIN(xb_ld(&bar[XB_XGEN(b.x)]) == gen, bar);
.LBB0_567:
	global_load_dword v2, v0, s[18:19] sc1
	s_add_i32 s6, s6, 1
	s_mov_b64 s[26:27], -1
	s_waitcnt vmcnt(0)
	v_cmp_ge_u32_e32 vcc, v2, v1
	s_orn2_b64 s[24:25], vcc, exec
	s_branch .LBB0_564

; __device__ __forceinline__ unsigned xb_ld(unsigned* p)              { return __hip_atomic_load(p, __ATOMIC_RELAXED, __HIP_MEMORY_SCOPE_AGENT); }
; __device__ __forceinline__ unsigned xb_add(unsigned* p, unsigned v) { return __hip_atomic_fetch_add(p, v, __ATOMIC_RELAXED, __HIP_MEMORY_SCOPE_AGENT); }
; #define XB_SPIN(cond, bar) do { unsigned _sp = 0; while (cond) { __builtin_amdgcn_s_sleep(1); \
;     if ((++_sp & 255u) == 0u) { if (xb_ld(&(bar)[XB_TMO])) break; if (_sp > XB_SPIN_CAP) { atomicAdd(&(bar)[XB_TMO], 1u); break; } } } } while (0)
; __device__ __forceinline__ void xcd_barrier(const XcdBarrier& b) {
;     ...
;         const unsigned old = xb_add(&bar[XB_XSUB(b.x)], 1u);
;         const unsigned gen = old / nloc;
;         if (old + 1u == (gen + 1u) * nloc) {
;             __builtin_amdgcn_fence(__ATOMIC_RELEASE, "agent");
;             asm volatile("s_waitcnt vmcnt(0)" ::: "memory");
;             const unsigned og = xb_add(&bar[XB_TOP], 1u);
;             const unsigned tg = og / nx;
;             if (og + 1u == (tg + 1u) * nx) xb_add(&bar[XB_TOPGEN], 1u);
;             else XB_SPIN(xb_ld(&bar[XB_TOPGEN]) == tg, bar);
;             __builtin_amdgcn_fence(__ATOMIC_ACQUIRE, "agent");
;             xb_add(&bar[XB_XGEN(b.x)], 1u);
;             asm volatile("s_waitcnt vmcnt(0)" ::: "memory");
;         } else {
;             XB_SPIN(xb_ld(&bar[XB_XGEN(b.x)]) == gen, bar);
;             __builtin_amdgcn_fence(__ATOMIC_ACQUIRE, "agent");
;             asm volatile("s_waitcnt vmcnt(0)" ::: "memory");
;         }
.LBB0_2049:
	s_or_b64 exec, exec, s[12:13]
	v_cvt_f32_u32_e32 v4, v2
	s_waitcnt vmcnt(0)
	v_readfirstlane_b32 s10, v3
	v_sub_u32_e32 v3, 0, v2
	v_rcp_iflag_f32_e32 v4, v4
	v_add_u32_e32 v5, s10, v1
	v_mul_f32_e32 v4, 0x4f7ffffe, v4
	v_cvt_u32_f32_e32 v4, v4
	v_mul_lo_u32 v1, v3, v4
	v_mul_hi_u32 v1, v4, v1
	v_add_u32_e32 v1, v4, v1
	v_mul_hi_u32 v1, v5, v1
	v_mul_lo_u32 v3, v1, v2
	v_sub_u32_e32 v3, v5, v3
	v_add_u32_e32 v4, 1, v1
	v_cmp_ge_u32_e32 vcc, v3, v2
	s_nop 1
	v_cndmask_b32_e32 v1, v1, v4, vcc
	v_sub_u32_e32 v4, v3, v2
	v_cndmask_b32_e32 v3, v3, v4, vcc
	v_add_u32_e32 v4, 1, v1
	v_cmp_ge_u32_e32 vcc, v3, v2
	v_add_u32_e32 v3, 1, v5
	s_nop 0
	v_cndmask_b32_e32 v1, v1, v4, vcc
	v_mul_lo_u32 v4, v2, v1
	v_add_u32_e32 v2, v4, v2
	v_cmp_ne_u32_e32 vcc, v3, v2
	s_cbranch_vccnz .Lxb_nl_13
	buffer_wbl2 sc1
	s_waitcnt vmcnt(0) lgkmcnt(0)
	v_mov_b32_e32 v3, 0x3400
	v_mov_b32_e32 v2, 1
	global_atomic_add v3, v2, s[48:49]
.Lxb_nl_13:
	s_mov_b64 vcc, exec
	s_and_saveexec_b64 s[10:11], vcc
	s_xor_b64 s[10:11], exec, s[10:11]
	s_cbranch_execz .LBB0_2063
	s_waitcnt lgkmcnt(0)
	v_add_u32_e32 v1, 1, v1
	v_mul_lo_u32 v1, v1, v0
	v_mov_b32_e32 v0, 0x3400
	global_load_dword v0, v0, s[48:49] sc1
	s_add_u32 s14, s48, 0x3400
	s_addc_u32 s15, s49, 0
	s_waitcnt vmcnt(0)
	v_cmp_lt_u32_e32 vcc, v0, v1
	s_and_saveexec_b64 s[12:13], vcc
	s_cbranch_execz .LBB0_2062
	s_mov_b32 s26, 1
	s_mov_b64 s[16:17], 0
	v_mov_b32_e32 v0, 0
	s_branch .LBB0_2053

; __device__ __forceinline__ unsigned xb_ld(unsigned* p)              { return __hip_atomic_load(p, __ATOMIC_RELAXED, __HIP_MEMORY_SCOPE_AGENT); }
; #define XB_SPIN(cond, bar) do { unsigned _sp = 0; while (cond) { __builtin_amdgcn_s_sleep(1); \
;     if ((++_sp & 255u) == 0u) { if (xb_ld(&(bar)[XB_TMO])) break; if (_sp > XB_SPIN_CAP) { atomicAdd(&(bar)[XB_TMO], 1u); break; } } } } while (0)
; __device__ __forceinline__ void xcd_barrier(const XcdBarrier& b) {
;     ...
;             XB_SPIN(xb_ld(&bar[XB_XGEN(b.x)]) == gen, bar);
.LBB0_2055:
	global_load_dword v2, v0, s[14:15] sc1
	s_add_i32 s26, s26, 1
	s_mov_b64 s[22:23], -1
	s_waitcnt vmcnt(0)
	v_cmp_ge_u32_e32 vcc, v2, v1
	s_orn2_b64 s[20:21], vcc, exec
	s_branch .LBB0_2052

; __device__ __forceinline__ unsigned xb_ld(unsigned* p)              { return __hip_atomic_load(p, __ATOMIC_RELAXED, __HIP_MEMORY_SCOPE_AGENT); }
; __device__ __forceinline__ unsigned xb_add(unsigned* p, unsigned v) { return __hip_atomic_fetch_add(p, v, __ATOMIC_RELAXED, __HIP_MEMORY_SCOPE_AGENT); }
; #define XB_SPIN(cond, bar) do { unsigned _sp = 0; while (cond) { __builtin_amdgcn_s_sleep(1); \
;     if ((++_sp & 255u) == 0u) { if (xb_ld(&(bar)[XB_TMO])) break; if (_sp > XB_SPIN_CAP) { atomicAdd(&(bar)[XB_TMO], 1u); break; } } } } while (0)
; __device__ __forceinline__ void xcd_barrier(const XcdBarrier& b) {
;     ...
;         const unsigned old = xb_add(&bar[XB_XSUB(b.x)], 1u);
;         const unsigned gen = old / nloc;
;         if (old + 1u == (gen + 1u) * nloc) {
;             __builtin_amdgcn_fence(__ATOMIC_RELEASE, "agent");
;             asm volatile("s_waitcnt vmcnt(0)" ::: "memory");
;             const unsigned og = xb_add(&bar[XB_TOP], 1u);
;             const unsigned tg = og / nx;
;             if (og + 1u == (tg + 1u) * nx) xb_add(&bar[XB_TOPGEN], 1u);
;             else XB_SPIN(xb_ld(&bar[XB_TOPGEN]) == tg, bar);
;             __builtin_amdgcn_fence(__ATOMIC_ACQUIRE, "agent");
;             xb_add(&bar[XB_XGEN(b.x)], 1u);
;             asm volatile("s_waitcnt vmcnt(0)" ::: "memory");
;         } else {
;             XB_SPIN(xb_ld(&bar[XB_XGEN(b.x)]) == gen, bar);
;             __builtin_amdgcn_fence(__ATOMIC_ACQUIRE, "agent");
;             asm volatile("s_waitcnt vmcnt(0)" ::: "memory");
;         }
.LBB0_2285:
	s_or_b64 exec, exec, s[10:11]
	v_cvt_f32_u32_e32 v4, v2
	s_waitcnt vmcnt(0)
	v_readfirstlane_b32 s3, v3
	v_sub_u32_e32 v3, 0, v2
	v_rcp_iflag_f32_e32 v4, v4
	v_add_u32_e32 v5, s3, v1
	v_mul_f32_e32 v4, 0x4f7ffffe, v4
	v_cvt_u32_f32_e32 v4, v4
	v_mul_lo_u32 v1, v3, v4
	v_mul_hi_u32 v1, v4, v1
	v_add_u32_e32 v1, v4, v1
	v_mul_hi_u32 v1, v5, v1
	v_mul_lo_u32 v3, v1, v2
	v_sub_u32_e32 v3, v5, v3
	v_add_u32_e32 v4, 1, v1
	v_cmp_ge_u32_e32 vcc, v3, v2
	s_nop 1
	v_cndmask_b32_e32 v1, v1, v4, vcc
	v_sub_u32_e32 v4, v3, v2
	v_cndmask_b32_e32 v3, v3, v4, vcc
	v_add_u32_e32 v4, 1, v1
	v_cmp_ge_u32_e32 vcc, v3, v2
	v_add_u32_e32 v3, 1, v5
	s_nop 0
	v_cndmask_b32_e32 v1, v1, v4, vcc
	v_mul_lo_u32 v4, v2, v1
	v_add_u32_e32 v2, v4, v2
	v_cmp_ne_u32_e32 vcc, v3, v2
	s_cbranch_vccnz .Lxb_nl_14
	buffer_wbl2 sc1
	s_waitcnt vmcnt(0) lgkmcnt(0)
	v_mov_b32_e32 v3, 0x3400
	v_mov_b32_e32 v2, 1
	global_atomic_add v3, v2, s[48:49]
.Lxb_nl_14:
	s_mov_b64 vcc, exec
	s_and_saveexec_b64 s[8:9], vcc
	s_xor_b64 s[8:9], exec, s[8:9]
	s_cbranch_execz .LBB0_2299
	s_waitcnt lgkmcnt(0)
	v_add_u32_e32 v1, 1, v1
	v_mul_lo_u32 v1, v1, v0
	v_mov_b32_e32 v0, 0x3400
	global_load_dword v0, v0, s[48:49] sc1
	s_add_u32 s12, s48, 0x3400
	s_addc_u32 s13, s49, 0
	s_waitcnt vmcnt(0)
	v_cmp_lt_u32_e32 vcc, v0, v1
	s_and_saveexec_b64 s[10:11], vcc
	s_cbranch_execz .LBB0_2298
	s_mov_b32 s3, 1
	s_mov_b64 s[14:15], 0
	v_mov_b32_e32 v0, 0
	s_branch .LBB0_2289

; __device__ __forceinline__ unsigned xb_ld(unsigned* p)              { return __hip_atomic_load(p, __ATOMIC_RELAXED, __HIP_MEMORY_SCOPE_AGENT); }
; #define XB_SPIN(cond, bar) do { unsigned _sp = 0; while (cond) { __builtin_amdgcn_s_sleep(1); \
;     if ((++_sp & 255u) == 0u) { if (xb_ld(&(bar)[XB_TMO])) break; if (_sp > XB_SPIN_CAP) { atomicAdd(&(bar)[XB_TMO], 1u); break; } } } } while (0)
; __device__ __forceinline__ void xcd_barrier(const XcdBarrier& b) {
;     ...
;             XB_SPIN(xb_ld(&bar[XB_XGEN(b.x)]) == gen, bar);
.LBB0_2291:
	global_load_dword v2, v0, s[12:13] sc1
	s_add_i32 s3, s3, 1
	s_mov_b64 s[20:21], -1
	s_waitcnt vmcnt(0)
	v_cmp_ge_u32_e32 vcc, v2, v1
	s_orn2_b64 s[18:19], vcc, exec
	s_branch .LBB0_2288
